# c39 + gemm1 K-loop: counted lgkmcnt waits per A-fragment (MFMAs start after the first 5 of 12 fragment reads instead of all 12; tail groups reordered by B fragment)
# baseline (speedup 1.0000x reference)
; template <bool LOWREG = false>
; __device__ __forceinline__ void gemm_core(const bf16_t* __restrict__ A, int lda, const bf16_t* __restrict__ Bt, int ldb, int K, f32x4 (&acc)[8][4], unsigned char* smem, int tid) {
;     ...
;     for (int kt = 0; kt < nk; ++kt) {
;         const int st = kt & 1;
;         const bool more = kt + 1 < nk;
;         const unsigned char* sb = smem + st * G_STAGE;
;         if constexpr (!LOWREG) {
; #pragma unroll
;         for (int ks = 0; ks < 2; ++ks) {
;             bf16x8 bfr[4], af[8];
;             const int co = ((ks * 4 + kq) ^ swz) * 16;
; #pragma unroll
;             for (int ni = 0; ni < 4; ++ni) bfr[ni] = *(const bf16x8*)(sb + boff + ni * 2048 + co);
; #pragma unroll
;             for (int mi = 0; mi < 8; ++mi) af[mi] = *(const bf16x8*)(sb + aoff + mi * 2048 + co);
;             if (more) { G_ISSUE1(kt + 1, st ^ 1, ks * 2); G_ISSUE1(kt + 1, st ^ 1, ks * 2 + 1); }
;             __builtin_amdgcn_sched_barrier(0);
;             __builtin_amdgcn_s_setprio(1);
; #pragma unroll
;             for (int mi = 0; mi < 8; ++mi)
; #pragma unroll
;                 for (int ni = 0; ni < 4; ++ni) acc[mi][ni] = __builtin_amdgcn_mfma_f32_16x16x32_bf16(bfr[ni], af[mi], acc[mi][ni], 0, 0, 0);
;             __builtin_amdgcn_s_setprio(0);
;             __builtin_amdgcn_sched_barrier(0);
;         }
.LBB0_255:
	s_and_b32 s16, s12, 0x10000
	s_add_i32 s17, s16, 0
	s_xor_b32 s16, s16, 0x10000
	v_add_u32_e32 v80, s17, v147
	v_add_u32_e32 v179, s17, v149
	s_add_i32 s16, s9, s16
	v_add_u32_e32 v162, v80, v148
	v_add_u32_e32 v196, v179, v148
	v_lshl_add_u64 v[200:201], v[130:131], 0, s[38:39]
	s_mov_b32 m0, s16
	ds_read_b128 v[150:153], v162 offset:32768
	ds_read_b128 v[154:157], v162 offset:34816
	ds_read_b128 v[158:161], v162 offset:36864
	ds_read_b128 v[162:165], v162 offset:38912
	ds_read_b128 v[166:169], v196
	ds_read_b128 v[170:173], v196 offset:2048
	ds_read_b128 v[174:177], v196 offset:4096
	ds_read_b128 v[180:183], v196 offset:6144
	ds_read_b128 v[184:187], v196 offset:8192
	ds_read_b128 v[188:191], v196 offset:10240
	ds_read_b128 v[192:195], v196 offset:12288
	ds_read_b128 v[196:199], v196 offset:14336
	global_load_lds_dwordx4 v[200:201], off
	v_lshl_add_u64 v[200:201], v[138:139], 0, s[38:39]
	s_add_i32 m0, s16, 0x8000
	s_nop 0
	global_load_lds_dwordx4 v[200:201], off
	v_lshl_add_u64 v[200:201], v[132:133], 0, s[38:39]
	s_add_i32 m0, s16, 0x2000
	s_nop 0
	global_load_lds_dwordx4 v[200:201], off
	v_lshl_add_u64 v[200:201], v[140:141], 0, s[38:39]
	s_add_i32 m0, s16, 0xa000
	s_nop 0
	global_load_lds_dwordx4 v[200:201], off
	s_cmp_lg_u32 s101, 0
	s_cbranch_scc1 .Lg1_dtalt1
	s_setprio 1
	s_waitcnt lgkmcnt(7)
	v_mfma_f32_16x16x32_bf16 v[126:129], v[150:153], v[166:169], v[126:129]
	v_mfma_f32_16x16x32_bf16 v[122:125], v[154:157], v[166:169], v[122:125]
	v_mfma_f32_16x16x32_bf16 v[118:121], v[158:161], v[166:169], v[118:121]
	v_mfma_f32_16x16x32_bf16 v[114:117], v[162:165], v[166:169], v[114:117]
	s_waitcnt lgkmcnt(6)
	v_mfma_f32_16x16x32_bf16 v[110:113], v[150:153], v[170:173], v[110:113]
	v_mfma_f32_16x16x32_bf16 v[106:109], v[154:157], v[170:173], v[106:109]
	v_mfma_f32_16x16x32_bf16 v[102:105], v[158:161], v[170:173], v[102:105]
	v_mfma_f32_16x16x32_bf16 v[98:101], v[162:165], v[170:173], v[98:101]
	s_waitcnt lgkmcnt(5)
	v_mfma_f32_16x16x32_bf16 v[94:97], v[150:153], v[174:177], v[94:97]
	v_mfma_f32_16x16x32_bf16 v[90:93], v[154:157], v[174:177], v[90:93]
	v_mfma_f32_16x16x32_bf16 v[86:89], v[158:161], v[174:177], v[86:89]
	v_mfma_f32_16x16x32_bf16 v[82:85], v[162:165], v[174:177], v[82:85]
	s_waitcnt lgkmcnt(4)
	v_mfma_f32_16x16x32_bf16 v[76:79], v[150:153], v[180:183], v[76:79]
	v_mfma_f32_16x16x32_bf16 v[72:75], v[154:157], v[180:183], v[72:75]
	v_mfma_f32_16x16x32_bf16 v[68:71], v[158:161], v[180:183], v[68:71]
	v_mfma_f32_16x16x32_bf16 v[64:67], v[162:165], v[180:183], v[64:67]
	s_waitcnt lgkmcnt(3)
	v_mfma_f32_16x16x32_bf16 v[60:63], v[150:153], v[184:187], v[60:63]
	v_mfma_f32_16x16x32_bf16 v[56:59], v[154:157], v[184:187], v[56:59]
	v_mfma_f32_16x16x32_bf16 v[52:55], v[158:161], v[184:187], v[52:55]
	v_mfma_f32_16x16x32_bf16 v[48:51], v[162:165], v[184:187], v[48:51]
	s_waitcnt lgkmcnt(2)
	v_mfma_f32_16x16x32_bf16 v[44:47], v[150:153], v[188:191], v[44:47]
	v_mfma_f32_16x16x32_bf16 v[40:43], v[154:157], v[188:191], v[40:43]
	v_mfma_f32_16x16x32_bf16 v[36:39], v[158:161], v[188:191], v[36:39]
	v_mfma_f32_16x16x32_bf16 v[32:35], v[162:165], v[188:191], v[32:35]
	s_waitcnt lgkmcnt(1)
	v_mfma_f32_16x16x32_bf16 v[28:31], v[150:153], v[192:195], v[28:31]
	v_mfma_f32_16x16x32_bf16 v[24:27], v[154:157], v[192:195], v[24:27]
	v_mfma_f32_16x16x32_bf16 v[20:23], v[158:161], v[192:195], v[20:23]
	v_mfma_f32_16x16x32_bf16 v[16:19], v[162:165], v[192:195], v[16:19]
	s_waitcnt lgkmcnt(0)
	v_mfma_f32_16x16x32_bf16 v[12:15], v[150:153], v[196:199], v[12:15]
	v_mfma_f32_16x16x32_bf16 v[8:11], v[154:157], v[196:199], v[8:11]
	v_mfma_f32_16x16x32_bf16 v[4:7], v[158:161], v[196:199], v[4:7]
	v_mfma_f32_16x16x32_bf16 v[0:3], v[162:165], v[196:199], v[0:3]
	s_setprio 0
.Lg1_dtskip1:
	s_waitcnt lgkmcnt(0)
	v_add_u32_e32 v80, v80, v146
	ds_read_b128 v[150:153], v80 offset:32768
	ds_read_b128 v[154:157], v80 offset:34816
	ds_read_b128 v[158:161], v80 offset:36864
	ds_read_b128 v[162:165], v80 offset:38912
	v_add_u32_e32 v80, v179, v146
	v_lshl_add_u64 v[200:201], v[134:135], 0, s[38:39]
	s_add_i32 m0, s16, 0x4000
	ds_read_b128 v[166:169], v80
	ds_read_b128 v[170:173], v80 offset:2048
	ds_read_b128 v[174:177], v80 offset:4096
	ds_read_b128 v[180:183], v80 offset:6144
	ds_read_b128 v[184:187], v80 offset:8192
	ds_read_b128 v[188:191], v80 offset:10240
	ds_read_b128 v[192:195], v80 offset:12288
	ds_read_b128 v[196:199], v80 offset:14336
	global_load_lds_dwordx4 v[200:201], off
	v_lshl_add_u64 v[200:201], v[142:143], 0, s[38:39]
	s_add_i32 m0, s16, 0xc000
	s_nop 0
	global_load_lds_dwordx4 v[200:201], off
	v_lshl_add_u64 v[200:201], v[136:137], 0, s[38:39]
	s_add_i32 m0, s16, 0x6000
	s_nop 0
	global_load_lds_dwordx4 v[200:201], off
	v_lshl_add_u64 v[200:201], v[144:145], 0, s[38:39]
	s_add_i32 m0, s16, 0xe000
	s_nop 0
	global_load_lds_dwordx4 v[200:201], off
	s_cmp_lg_u32 s101, 0
	s_cbranch_scc1 .Lg1_dtalt2
; template <bool LOWREG = false>
; __device__ __forceinline__ void gemm_core(const bf16_t* __restrict__ A, int lda, const bf16_t* __restrict__ Bt, int ldb, int K, f32x4 (&acc)[8][4], unsigned char* smem, int tid) {
;     ...
;     for (int kt = 0; kt < nk; ++kt) {
;         const int st = kt & 1;
;         const bool more = kt + 1 < nk;
;         const unsigned char* sb = smem + st * G_STAGE;
;         if constexpr (!LOWREG) {
; #pragma unroll
;         for (int ks = 0; ks < 2; ++ks) {
;             bf16x8 bfr[4], af[8];
;             const int co = ((ks * 4 + kq) ^ swz) * 16;
; #pragma unroll
;             for (int ni = 0; ni < 4; ++ni) bfr[ni] = *(const bf16x8*)(sb + boff + ni * 2048 + co);
; #pragma unroll
;             for (int mi = 0; mi < 8; ++mi) af[mi] = *(const bf16x8*)(sb + aoff + mi * 2048 + co);
;             if (more) { G_ISSUE1(kt + 1, st ^ 1, ks * 2); G_ISSUE1(kt + 1, st ^ 1, ks * 2 + 1); }
;             __builtin_amdgcn_sched_barrier(0);
;             __builtin_amdgcn_s_setprio(1);
; #pragma unroll
;             for (int mi = 0; mi < 8; ++mi)
; #pragma unroll
;                 for (int ni = 0; ni < 4; ++ni) acc[mi][ni] = __builtin_amdgcn_mfma_f32_16x16x32_bf16(bfr[ni], af[mi], acc[mi][ni], 0, 0, 0);
;             __builtin_amdgcn_s_setprio(0);
;             __builtin_amdgcn_sched_barrier(0);
;         }
;         } else {
; #pragma unroll
;         for (int ks = 0; ks < 2; ++ks) {
;             bf16x8 bfr[4];
;             const int co = ((ks * 4 + kq) ^ swz) * 16;
; #pragma unroll
;             for (int ni = 0; ni < 4; ++ni) bfr[ni] = *(const bf16x8*)(sb + boff + ni * 2048 + co);
; #pragma unroll
;             for (int mh = 0; mh < 2; ++mh) {
;                 bf16x8 af[4];
; #pragma unroll
;                 for (int mi = 0; mi < 4; ++mi) af[mi] = *(const bf16x8*)(sb + aoff + (mh * 4 + mi) * 2048 + co);
;                 if (more) G_ISSUE1(kt + 1, st ^ 1, ks * 2 + mh);
;                 __builtin_amdgcn_sched_barrier(0);
;                 __builtin_amdgcn_s_setprio(1);
; #pragma unroll
;                 for (int mi = 0; mi < 4; ++mi)
; #pragma unroll
;                     for (int ni = 0; ni < 4; ++ni) acc[mh * 4 + mi][ni] = __builtin_amdgcn_mfma_f32_16x16x32_bf16(bfr[ni], af[mi], acc[mh * 4 + mi][ni], 0, 0, 0);
;                 __builtin_amdgcn_s_setprio(0);
;                 __builtin_amdgcn_sched_barrier(0);
;             }
;         }
	s_setprio 1
	s_waitcnt lgkmcnt(7)
	v_mfma_f32_16x16x32_bf16 v[126:129], v[150:153], v[166:169], v[126:129]
	v_mfma_f32_16x16x32_bf16 v[122:125], v[154:157], v[166:169], v[122:125]
	v_mfma_f32_16x16x32_bf16 v[118:121], v[158:161], v[166:169], v[118:121]
	v_mfma_f32_16x16x32_bf16 v[114:117], v[162:165], v[166:169], v[114:117]
	s_waitcnt lgkmcnt(6)
	v_mfma_f32_16x16x32_bf16 v[110:113], v[150:153], v[170:173], v[110:113]
	v_mfma_f32_16x16x32_bf16 v[106:109], v[154:157], v[170:173], v[106:109]
	v_mfma_f32_16x16x32_bf16 v[102:105], v[158:161], v[170:173], v[102:105]
	v_mfma_f32_16x16x32_bf16 v[98:101], v[162:165], v[170:173], v[98:101]
	s_waitcnt lgkmcnt(5)
	v_mfma_f32_16x16x32_bf16 v[94:97], v[150:153], v[174:177], v[94:97]
	v_mfma_f32_16x16x32_bf16 v[90:93], v[154:157], v[174:177], v[90:93]
	v_mfma_f32_16x16x32_bf16 v[86:89], v[158:161], v[174:177], v[86:89]
	v_mfma_f32_16x16x32_bf16 v[82:85], v[162:165], v[174:177], v[82:85]
	s_waitcnt lgkmcnt(4)
	v_mfma_f32_16x16x32_bf16 v[76:79], v[150:153], v[180:183], v[76:79]
	v_mfma_f32_16x16x32_bf16 v[72:75], v[154:157], v[180:183], v[72:75]
	v_mfma_f32_16x16x32_bf16 v[68:71], v[158:161], v[180:183], v[68:71]
	v_mfma_f32_16x16x32_bf16 v[64:67], v[162:165], v[180:183], v[64:67]
	s_waitcnt lgkmcnt(3)
	v_mfma_f32_16x16x32_bf16 v[60:63], v[150:153], v[184:187], v[60:63]
	v_mfma_f32_16x16x32_bf16 v[56:59], v[154:157], v[184:187], v[56:59]
	v_mfma_f32_16x16x32_bf16 v[52:55], v[158:161], v[184:187], v[52:55]
	v_mfma_f32_16x16x32_bf16 v[48:51], v[162:165], v[184:187], v[48:51]
	s_waitcnt lgkmcnt(2)
	v_mfma_f32_16x16x32_bf16 v[44:47], v[150:153], v[188:191], v[44:47]
	v_mfma_f32_16x16x32_bf16 v[40:43], v[154:157], v[188:191], v[40:43]
	v_mfma_f32_16x16x32_bf16 v[36:39], v[158:161], v[188:191], v[36:39]
	v_mfma_f32_16x16x32_bf16 v[32:35], v[162:165], v[188:191], v[32:35]
	s_waitcnt lgkmcnt(1)
	v_mfma_f32_16x16x32_bf16 v[28:31], v[150:153], v[192:195], v[28:31]
	v_mfma_f32_16x16x32_bf16 v[24:27], v[154:157], v[192:195], v[24:27]
	v_mfma_f32_16x16x32_bf16 v[20:23], v[158:161], v[192:195], v[20:23]
	v_mfma_f32_16x16x32_bf16 v[16:19], v[162:165], v[192:195], v[16:19]
	s_waitcnt lgkmcnt(0)
	v_mfma_f32_16x16x32_bf16 v[12:15], v[150:153], v[196:199], v[12:15]
	v_mfma_f32_16x16x32_bf16 v[8:11], v[154:157], v[196:199], v[8:11]
	v_mfma_f32_16x16x32_bf16 v[4:7], v[158:161], v[196:199], v[4:7]
	v_mfma_f32_16x16x32_bf16 v[0:3], v[162:165], v[196:199], v[0:3]
	s_setprio 0
.Lg1_dtskip2:
	s_waitcnt lgkmcnt(0)
	s_add_i32 s12, s12, 0x10000
	s_waitcnt vmcnt(0)
	s_add_u32 s38, s38, 0x80
	s_addc_u32 s39, s39, 0
	s_cmpk_lg_i32 s38, 0x780
	s_waitcnt vmcnt(0)
	s_barrier
	s_cbranch_scc1 .LBB0_255
	s_add_i32 s9, 0, 0x10000
	v_add_u32_e32 v80, s9, v149
	v_add_u32_e32 v149, v80, v148
	ds_read_b128 v[130:133], v149 offset:14336
	ds_read_b128 v[134:137], v149 offset:12288
	ds_read_b128 v[138:141], v149 offset:10240
	ds_read_b128 v[142:145], v149 offset:8192
	ds_read_b128 v[150:153], v149 offset:6144
	ds_read_b128 v[154:157], v149 offset:4096
	ds_read_b128 v[158:161], v149 offset:2048
	ds_read_b128 v[162:165], v149
	v_add_u32_e32 v147, s9, v147
	v_add_u32_e32 v148, v147, v148
	ds_read_b128 v[166:169], v148 offset:38912
	ds_read_b128 v[170:173], v148 offset:36864
	ds_read_b128 v[174:177], v148 offset:34816
	ds_read_b128 v[180:183], v148 offset:32768
	s_cmp_lg_u32 s101, 0
	s_cbranch_scc1 .Lg1_dtalt3
	s_setprio 1
	s_waitcnt lgkmcnt(3)
	v_mfma_f32_16x16x32_bf16 v[114:117], v[166:169], v[162:165], v[114:117]
	v_mfma_f32_16x16x32_bf16 v[98:101], v[166:169], v[158:161], v[98:101]
	v_mfma_f32_16x16x32_bf16 v[82:85], v[166:169], v[154:157], v[82:85]
	v_mfma_f32_16x16x32_bf16 v[64:67], v[166:169], v[150:153], v[64:67]
	v_mfma_f32_16x16x32_bf16 v[48:51], v[166:169], v[142:145], v[48:51]
	v_mfma_f32_16x16x32_bf16 v[32:35], v[166:169], v[138:141], v[32:35]
	v_mfma_f32_16x16x32_bf16 v[16:19], v[166:169], v[134:137], v[16:19]
	v_mfma_f32_16x16x32_bf16 v[0:3], v[166:169], v[130:133], v[0:3]
	s_waitcnt lgkmcnt(2)
	v_mfma_f32_16x16x32_bf16 v[118:121], v[170:173], v[162:165], v[118:121]
	v_mfma_f32_16x16x32_bf16 v[102:105], v[170:173], v[158:161], v[102:105]
	v_mfma_f32_16x16x32_bf16 v[86:89], v[170:173], v[154:157], v[86:89]
	v_mfma_f32_16x16x32_bf16 v[68:71], v[170:173], v[150:153], v[68:71]
	v_mfma_f32_16x16x32_bf16 v[52:55], v[170:173], v[142:145], v[52:55]
	v_mfma_f32_16x16x32_bf16 v[36:39], v[170:173], v[138:141], v[36:39]
	v_mfma_f32_16x16x32_bf16 v[20:23], v[170:173], v[134:137], v[20:23]
	v_mfma_f32_16x16x32_bf16 v[4:7], v[170:173], v[130:133], v[4:7]
	s_waitcnt lgkmcnt(1)
	v_mfma_f32_16x16x32_bf16 v[122:125], v[174:177], v[162:165], v[122:125]
	v_mfma_f32_16x16x32_bf16 v[106:109], v[174:177], v[158:161], v[106:109]
	v_mfma_f32_16x16x32_bf16 v[90:93], v[174:177], v[154:157], v[90:93]
	v_mfma_f32_16x16x32_bf16 v[72:75], v[174:177], v[150:153], v[72:75]
	v_mfma_f32_16x16x32_bf16 v[56:59], v[174:177], v[142:145], v[56:59]
	v_mfma_f32_16x16x32_bf16 v[40:43], v[174:177], v[138:141], v[40:43]
	v_mfma_f32_16x16x32_bf16 v[24:27], v[174:177], v[134:137], v[24:27]
	v_mfma_f32_16x16x32_bf16 v[8:11], v[174:177], v[130:133], v[8:11]
	s_waitcnt lgkmcnt(0)
	v_mfma_f32_16x16x32_bf16 v[126:129], v[180:183], v[162:165], v[126:129]
	v_mfma_f32_16x16x32_bf16 v[110:113], v[180:183], v[158:161], v[110:113]
	v_mfma_f32_16x16x32_bf16 v[94:97], v[180:183], v[154:157], v[94:97]
	v_mfma_f32_16x16x32_bf16 v[76:79], v[180:183], v[150:153], v[76:79]
	v_mfma_f32_16x16x32_bf16 v[60:63], v[180:183], v[142:145], v[60:63]
	v_mfma_f32_16x16x32_bf16 v[44:47], v[180:183], v[138:141], v[44:47]
	v_mfma_f32_16x16x32_bf16 v[28:31], v[180:183], v[134:137], v[28:31]
	v_mfma_f32_16x16x32_bf16 v[12:15], v[180:183], v[130:133], v[12:15]
	s_setprio 0
; template <bool LOWREG = false>
; __device__ __forceinline__ void gemm_core(const bf16_t* __restrict__ A, int lda, const bf16_t* __restrict__ Bt, int ldb, int K, f32x4 (&acc)[8][4], unsigned char* smem, int tid) {
;     ...
; #pragma unroll
;         for (int ks = 0; ks < 2; ++ks) {
;             bf16x8 bfr[4], af[8];
;             const int co = ((ks * 4 + kq) ^ swz) * 16;
; #pragma unroll
;             for (int ni = 0; ni < 4; ++ni) bfr[ni] = *(const bf16x8*)(sb + boff + ni * 2048 + co);
; #pragma unroll
;             for (int mi = 0; mi < 8; ++mi) af[mi] = *(const bf16x8*)(sb + aoff + mi * 2048 + co);
;             if (more) { G_ISSUE1(kt + 1, st ^ 1, ks * 2); G_ISSUE1(kt + 1, st ^ 1, ks * 2 + 1); }
;             __builtin_amdgcn_sched_barrier(0);
;             __builtin_amdgcn_s_setprio(1);
; #pragma unroll
;             for (int mi = 0; mi < 8; ++mi)
; #pragma unroll
;                 for (int ni = 0; ni < 4; ++ni) acc[mi][ni] = __builtin_amdgcn_mfma_f32_16x16x32_bf16(bfr[ni], af[mi], acc[mi][ni], 0, 0, 0);
;             __builtin_amdgcn_s_setprio(0);
;             __builtin_amdgcn_sched_barrier(0);
;         }
.Lg1_dtskip3:
	s_waitcnt lgkmcnt(0)
	v_add_u32_e32 v80, v80, v146
	ds_read_b128 v[130:133], v80 offset:14336
	ds_read_b128 v[134:137], v80 offset:12288
	ds_read_b128 v[138:141], v80 offset:10240
	ds_read_b128 v[142:145], v80 offset:8192
	ds_read_b128 v[148:151], v80 offset:6144
	ds_read_b128 v[152:155], v80 offset:4096
	ds_read_b128 v[156:159], v80 offset:2048
	ds_read_b128 v[160:163], v80
	v_add_u32_e32 v80, v147, v146
	ds_read_b128 v[164:167], v80 offset:38912
	ds_read_b128 v[168:171], v80 offset:36864
	ds_read_b128 v[172:175], v80 offset:34816
	ds_read_b128 v[180:183], v80 offset:32768
	s_cmp_lg_u32 s101, 0
	s_cbranch_scc1 .Lg1_dtalt4
	s_setprio 1
	s_waitcnt lgkmcnt(3)
	v_mfma_f32_16x16x32_bf16 v[114:117], v[164:167], v[160:163], v[114:117]
	v_mfma_f32_16x16x32_bf16 v[98:101], v[164:167], v[156:159], v[98:101]
	v_mfma_f32_16x16x32_bf16 v[82:85], v[164:167], v[152:155], v[82:85]
	v_mfma_f32_16x16x32_bf16 v[64:67], v[164:167], v[148:151], v[64:67]
	v_mfma_f32_16x16x32_bf16 v[48:51], v[164:167], v[142:145], v[48:51]
	v_mfma_f32_16x16x32_bf16 v[32:35], v[164:167], v[138:141], v[32:35]
	v_mfma_f32_16x16x32_bf16 v[16:19], v[164:167], v[134:137], v[16:19]
	v_mfma_f32_16x16x32_bf16 v[0:3], v[164:167], v[130:133], v[0:3]
	s_waitcnt lgkmcnt(2)
	v_mfma_f32_16x16x32_bf16 v[118:121], v[168:171], v[160:163], v[118:121]
	v_mfma_f32_16x16x32_bf16 v[102:105], v[168:171], v[156:159], v[102:105]
	v_mfma_f32_16x16x32_bf16 v[86:89], v[168:171], v[152:155], v[86:89]
	v_mfma_f32_16x16x32_bf16 v[68:71], v[168:171], v[148:151], v[68:71]
	v_mfma_f32_16x16x32_bf16 v[52:55], v[168:171], v[142:145], v[52:55]
	v_mfma_f32_16x16x32_bf16 v[36:39], v[168:171], v[138:141], v[36:39]
	v_mfma_f32_16x16x32_bf16 v[20:23], v[168:171], v[134:137], v[20:23]
	v_mfma_f32_16x16x32_bf16 v[4:7], v[168:171], v[130:133], v[4:7]
	s_waitcnt lgkmcnt(1)
	v_mfma_f32_16x16x32_bf16 v[122:125], v[172:175], v[160:163], v[122:125]
	v_mfma_f32_16x16x32_bf16 v[106:109], v[172:175], v[156:159], v[106:109]
	v_mfma_f32_16x16x32_bf16 v[90:93], v[172:175], v[152:155], v[90:93]
	v_mfma_f32_16x16x32_bf16 v[72:75], v[172:175], v[148:151], v[72:75]
	v_mfma_f32_16x16x32_bf16 v[56:59], v[172:175], v[142:145], v[56:59]
	v_mfma_f32_16x16x32_bf16 v[40:43], v[172:175], v[138:141], v[40:43]
	v_mfma_f32_16x16x32_bf16 v[24:27], v[172:175], v[134:137], v[24:27]
	v_mfma_f32_16x16x32_bf16 v[8:11], v[172:175], v[130:133], v[8:11]
	s_waitcnt lgkmcnt(0)
	v_mfma_f32_16x16x32_bf16 v[126:129], v[180:183], v[160:163], v[126:129]
	v_mfma_f32_16x16x32_bf16 v[110:113], v[180:183], v[156:159], v[110:113]
	v_mfma_f32_16x16x32_bf16 v[94:97], v[180:183], v[152:155], v[94:97]
	v_mfma_f32_16x16x32_bf16 v[76:79], v[180:183], v[148:151], v[76:79]
	v_mfma_f32_16x16x32_bf16 v[60:63], v[180:183], v[142:145], v[60:63]
	v_mfma_f32_16x16x32_bf16 v[44:47], v[180:183], v[138:141], v[44:47]
	v_mfma_f32_16x16x32_bf16 v[28:31], v[180:183], v[134:137], v[28:31]
	v_mfma_f32_16x16x32_bf16 v[12:15], v[180:183], v[130:133], v[12:15]
	s_setprio 0
